# adds hand-written sliding-window + dilated band loops (packed f32 softmax, permlane32 reductions, thresholded rescale) to the FoX pair loop
# speedup vs baseline: 1.0090x; 1.0046x over previous
.Lband_entry:
	s_waitcnt vmcnt(0)
	v_lshlrev_b32_e32 v183, 2, v220
	v_add_u32_e32 v2, 0x10000, v183
	ds_write_b32 v183, v162 offset:0
	ds_write_b32 v183, v163 offset:2048
	ds_write_b32 v183, v164 offset:4096
	ds_write_b32 v183, v165 offset:6144
	ds_write_b32 v183, v166 offset:8192
	ds_write_b32 v183, v167 offset:10240
	ds_write_b32 v183, v168 offset:12288
	ds_write_b32 v183, v169 offset:14336
	ds_write_b32 v183, v170 offset:16384
	ds_write_b32 v183, v174 offset:18432
	ds_write_b32 v183, v175 offset:20480
	ds_write_b32 v183, v176 offset:22528
	ds_write_b32 v183, v177 offset:24576
	ds_write_b32 v183, v216 offset:26624
	ds_write_b32 v183, v217 offset:28672
	ds_write_b32 v183, v218 offset:30720
	ds_write_b32 v183, v219 offset:32768
	ds_write_b32 v183, v225 offset:34816
	ds_write_b32 v183, v226 offset:36864
	ds_write_b32 v183, v227 offset:38912
	ds_write_b32 v183, v236 offset:40960
	ds_write_b32 v183, v237 offset:43008
	ds_write_b32 v183, v249 offset:45056
	ds_write_b32 v183, v200 offset:47104
	ds_write_b32 v183, v201 offset:49152
	ds_write_b32 v183, v202 offset:51200
	ds_write_b32 v183, v203 offset:53248
	ds_write_b32 v183, v204 offset:55296
	ds_write_b32 v183, v205 offset:57344
	ds_write_b32 v183, v206 offset:59392
	ds_write_b32 v183, v207 offset:61440
	ds_write_b32 v183, v208 offset:63488
	ds_write_b32 v2, v209 offset:0
	ds_write_b32 v2, v210 offset:2048
	ds_write_b32 v2, v211 offset:4096
	ds_write_b32 v2, v212 offset:6144
	ds_write_b32 v2, v213 offset:8192
	ds_write_b32 v2, v214 offset:10240
	ds_write_b32 v2, v215 offset:12288
	v_lshrrev_b32_e32 v183, 6, v220
	v_lshlrev_b32_e32 v183, 8, v183
	v_add_u32_e32 v183, 0x13800, v183
	v_mov_b32_e32 v3, s2
	ds_write_b32 v183, v3 offset:0
	v_mov_b32_e32 v3, s3
	ds_write_b32 v183, v3 offset:4
	v_mov_b32_e32 v3, s4
	ds_write_b32 v183, v3 offset:8
	v_mov_b32_e32 v3, s5
	ds_write_b32 v183, v3 offset:12
	v_mov_b32_e32 v3, s6
	ds_write_b32 v183, v3 offset:16
	v_mov_b32_e32 v3, s7
	ds_write_b32 v183, v3 offset:20
	v_mov_b32_e32 v3, s8
	ds_write_b32 v183, v3 offset:24
	v_mov_b32_e32 v3, s9
	ds_write_b32 v183, v3 offset:28
	v_mov_b32_e32 v3, s10
	ds_write_b32 v183, v3 offset:32
	v_mov_b32_e32 v3, s11
	ds_write_b32 v183, v3 offset:36
	v_mov_b32_e32 v3, s12
	ds_write_b32 v183, v3 offset:40
	v_mov_b32_e32 v3, s13
	ds_write_b32 v183, v3 offset:44
	v_mov_b32_e32 v3, s14
	ds_write_b32 v183, v3 offset:48
	v_mov_b32_e32 v3, s15
	ds_write_b32 v183, v3 offset:52
	v_mov_b32_e32 v3, s16
	ds_write_b32 v183, v3 offset:56
	v_mov_b32_e32 v3, s17
	ds_write_b32 v183, v3 offset:60
	v_mov_b32_e32 v3, s18
	ds_write_b32 v183, v3 offset:64
	v_mov_b32_e32 v3, s19
	ds_write_b32 v183, v3 offset:68
	v_mov_b32_e32 v3, s20
	ds_write_b32 v183, v3 offset:72
	v_mov_b32_e32 v3, s21
	ds_write_b32 v183, v3 offset:76
	v_mov_b32_e32 v3, s22
	ds_write_b32 v183, v3 offset:80
	v_mov_b32_e32 v3, s23
	ds_write_b32 v183, v3 offset:84
	v_mov_b32_e32 v3, s24
	ds_write_b32 v183, v3 offset:88
	v_mov_b32_e32 v3, s25
	ds_write_b32 v183, v3 offset:92
	v_mov_b32_e32 v3, s26
	ds_write_b32 v183, v3 offset:96
	v_mov_b32_e32 v3, s27
	ds_write_b32 v183, v3 offset:100
	v_mov_b32_e32 v3, s28
	ds_write_b32 v183, v3 offset:104
	v_mov_b32_e32 v3, s29
	ds_write_b32 v183, v3 offset:108
	v_mov_b32_e32 v3, s30
	ds_write_b32 v183, v3 offset:112
	v_mov_b32_e32 v3, s34
	ds_write_b32 v183, v3 offset:116
	v_mov_b32_e32 v3, s35
	ds_write_b32 v183, v3 offset:120
	v_mov_b32_e32 v3, s36
	ds_write_b32 v183, v3 offset:124
	v_mov_b32_e32 v3, s37
	ds_write_b32 v183, v3 offset:128
	v_mov_b32_e32 v3, s38
	ds_write_b32 v183, v3 offset:132
	v_mov_b32_e32 v3, s39
	ds_write_b32 v183, v3 offset:136
	v_mov_b32_e32 v3, s40
	ds_write_b32 v183, v3 offset:140
	v_mov_b32_e32 v3, s41
	ds_write_b32 v183, v3 offset:144
	v_mov_b32_e32 v3, s42
	ds_write_b32 v183, v3 offset:148
	v_mov_b32_e32 v3, s43
	ds_write_b32 v183, v3 offset:152
	v_mov_b32_e32 v3, s44
	ds_write_b32 v183, v3 offset:156
	v_mov_b32_e32 v3, s45
	ds_write_b32 v183, v3 offset:160
	v_mov_b32_e32 v3, s46
	ds_write_b32 v183, v3 offset:164
	v_mov_b32_e32 v3, s47
	ds_write_b32 v183, v3 offset:168
	v_mov_b32_e32 v3, s48
	ds_write_b32 v183, v3 offset:172
	v_mov_b32_e32 v3, s49
	ds_write_b32 v183, v3 offset:176
	s_load_dwordx2 s[18:19], s[70:71], 0x98
	s_load_dwordx2 s[20:21], s[70:71], 0x58
	v_and_b32_e32 v163, 31, v173
	v_lshrrev_b32_e32 v164, 5, v173
	v_lshlrev_b32_e32 v162, 4, v173
	v_mov_b32_e32 v227, 0xff800000
	v_lshlrev_b32_e32 v183, 2, v164
	v_sub_u32_e32 v170, v163, v183
	v_mov_b32_e32 v226, 0x3e38aa3b
	s_mov_b32 s0, s1
	s_waitcnt lgkmcnt(0)

.Lband_dec_done:
	s_mul_i32 s17, s23, 0x1600000
	s_add_u32 s2, s18, s17
	s_addc_u32 s3, s19, 0
	s_add_u32 s2, s2, 0x5600000
	s_addc_u32 s3, s3, 0
	s_lshl_b32 s11, 0x2c000, s9
	v_lshl_add_u32 v183, s8, 5, v163
	v_lshlrev_b32_e32 v183, s9, v183
	v_add_u32_e32 v176, s10, v183
	v_mul_u32_u24_e32 v177, 0x1600, v176
	v_add_u32_e32 v177, s13, v177
	v_lshl_add_u32 v177, v164, 4, v177
	global_load_dwordx4 v[130:133], v177, s[2:3]
	global_load_dwordx4 v[134:137], v177, s[2:3] offset:32
	global_load_dwordx4 v[138:141], v177, s[2:3] offset:64
	global_load_dwordx4 v[142:145], v177, s[2:3] offset:96
	v_lshlrev_b32_e32 v183, s9, v163
	v_add_u32_e32 v183, s10, v183
	v_mul_u32_u24_e32 v175, 0x1600, v183
	v_add_u32_e32 v175, s12, v175
	v_lshl_add_u32 v175, v164, 4, v175
	s_add_i32 s16, s8, -4
	s_max_i32 s16, s16, 0
	s_mul_i32 s17, s16, s11
	v_add_u32_e32 v177, s17, v175
	global_load_dwordx4 v[2:5], v177, s[2:3]
	global_load_dwordx4 v[6:9], v177, s[2:3] offset:32
	global_load_dwordx4 v[10:13], v177, s[2:3] offset:64
	global_load_dwordx4 v[14:17], v177, s[2:3] offset:96
	s_add_i32 s16, s8, -4
	s_max_i32 s16, s16, 0
	s_lshl_b32 s17, s16, 12
	v_add_u32_e32 v177, s17, v162
	global_load_dwordx4 v[82:85], v177, s[4:5]
	global_load_dwordx4 v[86:89], v177, s[4:5] offset:1024
	global_load_dwordx4 v[90:93], v177, s[4:5] offset:2048
	global_load_dwordx4 v[94:97], v177, s[4:5] offset:3072
	s_add_i32 s16, s8, -3
	s_max_i32 s16, s16, 0
	s_mul_i32 s17, s16, s11
	v_add_u32_e32 v177, s17, v175
	global_load_dwordx4 v[18:21], v177, s[2:3]
	global_load_dwordx4 v[22:25], v177, s[2:3] offset:32
	global_load_dwordx4 v[26:29], v177, s[2:3] offset:64
	global_load_dwordx4 v[30:33], v177, s[2:3] offset:96
	s_add_i32 s16, s8, -3
	s_max_i32 s16, s16, 0
	s_lshl_b32 s17, s16, 12
	v_add_u32_e32 v177, s17, v162
	global_load_dwordx4 v[98:101], v177, s[4:5]
	global_load_dwordx4 v[102:105], v177, s[4:5] offset:1024
	global_load_dwordx4 v[106:109], v177, s[4:5] offset:2048
	global_load_dwordx4 v[110:113], v177, s[4:5] offset:3072
	s_add_i32 s16, s8, -2
	s_max_i32 s16, s16, 0
	s_mul_i32 s17, s16, s11
	v_add_u32_e32 v177, s17, v175
	global_load_dwordx4 v[34:37], v177, s[2:3]
	global_load_dwordx4 v[38:41], v177, s[2:3] offset:32
	global_load_dwordx4 v[42:45], v177, s[2:3] offset:64
	global_load_dwordx4 v[46:49], v177, s[2:3] offset:96
	s_add_i32 s16, s8, -2
	s_max_i32 s16, s16, 0
	s_lshl_b32 s17, s16, 12
	v_add_u32_e32 v177, s17, v162
	global_load_dwordx4 v[114:117], v177, s[4:5]
	global_load_dwordx4 v[118:121], v177, s[4:5] offset:1024
	global_load_dwordx4 v[122:125], v177, s[4:5] offset:2048
	global_load_dwordx4 v[126:129], v177, s[4:5] offset:3072
	s_add_i32 s16, s8, -1
	s_max_i32 s16, s16, 0
	s_mul_i32 s17, s16, s11
	v_add_u32_e32 v177, s17, v175
	global_load_dwordx4 v[50:53], v177, s[2:3]
	global_load_dwordx4 v[54:57], v177, s[2:3] offset:32
	global_load_dwordx4 v[58:61], v177, s[2:3] offset:64
	global_load_dwordx4 v[62:65], v177, s[2:3] offset:96
	s_add_i32 s16, s8, 0
	s_max_i32 s16, s16, 0
	s_mul_i32 s17, s16, s11
	v_add_u32_e32 v177, s17, v175
	global_load_dwordx4 v[66:69], v177, s[2:3]
	global_load_dwordx4 v[70:73], v177, s[2:3] offset:32
	global_load_dwordx4 v[74:77], v177, s[2:3] offset:64
	global_load_dwordx4 v[78:81], v177, s[2:3] offset:96
	v_cvt_f32_i32_e32 v167, s24
	v_mul_f32_e32 v167, 0xbf2aaaab, v167
	v_exp_f32_e32 v167, v167
	v_cvt_f32_i32_e32 v168, v170
	v_mul_f32_e32 v167, 0x3fb8aa3b, v167
	v_ldexp_f32 v167, v167, s9
	v_mul_f32_e64 v168, -v167, v168
	v_mul_f32_e32 v200, 0x00000000, v167
	v_mul_f32_e32 v201, 0x3f800000, v167
	v_mul_f32_e32 v202, 0x40000000, v167
	v_mul_f32_e32 v203, 0x40400000, v167
	v_mul_f32_e32 v204, 0x41000000, v167
	v_mul_f32_e32 v205, 0x41100000, v167
	v_mul_f32_e32 v206, 0x41200000, v167
	v_mul_f32_e32 v207, 0x41300000, v167
	v_mul_f32_e32 v208, 0x41800000, v167
	v_mul_f32_e32 v209, 0x41880000, v167
	v_mul_f32_e32 v210, 0x41900000, v167
	v_mul_f32_e32 v211, 0x41980000, v167
	v_mul_f32_e32 v212, 0x41c00000, v167
	v_mul_f32_e32 v213, 0x41c80000, v167
	v_mul_f32_e32 v214, 0x41d00000, v167
	v_mul_f32_e32 v215, 0x41d80000, v167
	v_readfirstlane_b32 s34, v200
	v_readfirstlane_b32 s35, v201
	v_readfirstlane_b32 s36, v202
	v_readfirstlane_b32 s37, v203
	v_readfirstlane_b32 s38, v204
	v_readfirstlane_b32 s39, v205
	v_readfirstlane_b32 s40, v206
	v_readfirstlane_b32 s41, v207
	v_readfirstlane_b32 s42, v208
	v_readfirstlane_b32 s43, v209
	v_readfirstlane_b32 s44, v210
	v_readfirstlane_b32 s45, v211
	v_readfirstlane_b32 s46, v212
	v_readfirstlane_b32 s47, v213
	v_readfirstlane_b32 s48, v214
	v_readfirstlane_b32 s49, v215
	v_add_u32_e32 v174, s15, v170
	v_lshlrev_b32_e32 v218, s14, v176
	v_lshl_add_u32 v218, v164, 3, v218
	v_lshlrev_b32_e32 v219, 4, v176
	v_mov_b32_e32 v165, 0xf149f2ca
	v_mov_b32_e32 v249, 0xf149f2ca
	v_mov_b32_e32 v166, 0
	v_mov_b32_e32 v146, 0
	v_mov_b32_e32 v147, 0
	v_mov_b32_e32 v148, 0
	v_mov_b32_e32 v149, 0
	v_mov_b32_e32 v150, 0
	v_mov_b32_e32 v151, 0
	v_mov_b32_e32 v152, 0
	v_mov_b32_e32 v153, 0
	v_mov_b32_e32 v154, 0
	v_mov_b32_e32 v155, 0
	v_mov_b32_e32 v156, 0
	v_mov_b32_e32 v157, 0
	v_mov_b32_e32 v158, 0
	v_mov_b32_e32 v159, 0
	v_mov_b32_e32 v160, 0
	v_mov_b32_e32 v161, 0
	v_mov_b32_e32 v184, 0
	v_mov_b32_e32 v185, 0
	v_mov_b32_e32 v186, 0
	v_mov_b32_e32 v187, 0
	v_mov_b32_e32 v188, 0
	v_mov_b32_e32 v189, 0
	v_mov_b32_e32 v190, 0
	v_mov_b32_e32 v191, 0
	v_mov_b32_e32 v192, 0
	v_mov_b32_e32 v193, 0
	v_mov_b32_e32 v194, 0
	v_mov_b32_e32 v195, 0
	v_mov_b32_e32 v196, 0
	v_mov_b32_e32 v197, 0
	v_mov_b32_e32 v198, 0
	v_mov_b32_e32 v199, 0
	s_cmp_lt_i32 s8, 4
	s_cbranch_scc1 .Lband_s0a
	s_waitcnt vmcnt(28)
	v_mfma_f32_32x32x16_bf16 v[200:215], v[2:5], v[130:133], 0
	v_mfma_f32_32x32x16_bf16 v[200:215], v[6:9], v[134:137], v[200:215]
	v_mfma_f32_32x32x16_bf16 v[200:215], v[10:13], v[138:141], v[200:215]
	v_mfma_f32_32x32x16_bf16 v[200:215], v[14:17], v[142:145], v[200:215]
.Lband_s0a:
	s_add_i32 s16, s8, -1
	s_max_i32 s16, s16, 0
	s_lshl_b32 s17, s16, 12
	v_add_u32_e32 v177, s17, v162
	global_load_dwordx4 v[2:5], v177, s[4:5]
	global_load_dwordx4 v[6:9], v177, s[4:5] offset:1024
	global_load_dwordx4 v[10:13], v177, s[4:5] offset:2048
	global_load_dwordx4 v[14:17], v177, s[4:5] offset:3072
	s_cmp_lt_i32 s8, 4
	s_cbranch_scc1 .Lband_s0b
	v_fmamk_f32 v169, v167, 0xc3000000, v168
	s_nop 7
	s_nop 4
	v_pk_fma_f32 v[200:201], v[200:201], v[226:227], s[34:35] op_sel_hi:[1,0,1]
	v_pk_fma_f32 v[202:203], v[202:203], v[226:227], s[36:37] op_sel_hi:[1,0,1]
	v_pk_fma_f32 v[204:205], v[204:205], v[226:227], s[38:39] op_sel_hi:[1,0,1]
	v_pk_fma_f32 v[206:207], v[206:207], v[226:227], s[40:41] op_sel_hi:[1,0,1]
	v_pk_fma_f32 v[208:209], v[208:209], v[226:227], s[42:43] op_sel_hi:[1,0,1]
	v_pk_fma_f32 v[210:211], v[210:211], v[226:227], s[44:45] op_sel_hi:[1,0,1]
	v_pk_fma_f32 v[212:213], v[212:213], v[226:227], s[46:47] op_sel_hi:[1,0,1]
	v_pk_fma_f32 v[214:215], v[214:215], v[226:227], s[48:49] op_sel_hi:[1,0,1]
	v_cmp_ge_i32_e64 s[16:17], 0, v174
	v_cmp_ge_i32_e64 s[22:23], 1, v174
	v_cmp_ge_i32_e64 s[24:25], 2, v174
	v_cmp_ge_i32_e64 s[28:29], 3, v174
	v_cmp_ge_i32_e32 vcc, 8, v174
	v_cndmask_b32_e64 v200, v227, v200, s[16:17]
	v_cndmask_b32_e64 v201, v227, v201, s[22:23]
	v_cndmask_b32_e64 v202, v227, v202, s[24:25]
	v_cndmask_b32_e64 v203, v227, v203, s[28:29]
	v_cndmask_b32_e64 v204, v227, v204, vcc
	v_cmp_ge_i32_e64 s[16:17], 9, v174
	v_cmp_ge_i32_e64 s[22:23], 10, v174
	v_cmp_ge_i32_e64 s[24:25], 11, v174
	v_cmp_ge_i32_e64 s[28:29], 16, v174
	v_cmp_ge_i32_e32 vcc, 17, v174
	v_cndmask_b32_e64 v205, v227, v205, s[16:17]
	v_cndmask_b32_e64 v206, v227, v206, s[22:23]
	v_cndmask_b32_e64 v207, v227, v207, s[24:25]
	v_cndmask_b32_e64 v208, v227, v208, s[28:29]
	v_cndmask_b32_e64 v209, v227, v209, vcc
	v_cmp_ge_i32_e64 s[16:17], 18, v174
	v_cmp_ge_i32_e64 s[22:23], 19, v174
	v_cmp_ge_i32_e64 s[24:25], 24, v174
	v_cmp_ge_i32_e64 s[28:29], 25, v174
	v_cmp_ge_i32_e32 vcc, 26, v174
	v_cndmask_b32_e64 v210, v227, v210, s[16:17]
	v_cndmask_b32_e64 v211, v227, v211, s[22:23]
	v_cndmask_b32_e64 v212, v227, v212, s[24:25]
	v_cndmask_b32_e64 v213, v227, v213, s[28:29]
	v_cndmask_b32_e64 v214, v227, v214, vcc
	v_cmp_ge_i32_e64 s[16:17], 27, v174
	s_nop 1
	v_cndmask_b32_e64 v215, v227, v215, s[16:17]
	v_max3_f32 v183, v200, v201, v202
	v_max3_f32 v225, v203, v204, v205
	v_max3_f32 v216, v206, v207, v208
	v_max3_f32 v217, v209, v210, v211
	v_max3_f32 v236, v212, v213, v214
	v_max3_f32 v183, v183, v225, v216
	v_max3_f32 v217, v217, v236, v215
	v_max_f32_e32 v183, v183, v217
	v_add_f32_e32 v183, v183, v169
	v_mov_b32_e32 v225, v183
	s_nop 1
	v_permlane32_swap_b32_e32 v225, v183
	v_max_f32_e32 v183, v183, v225
	v_cmp_lt_f32_e32 vcc, v249, v183
	s_cbranch_vccz .Lband_keep0
	v_max_f32_e32 v225, v165, v183
	v_sub_f32_e32 v216, v165, v225
	v_exp_f32_e32 v216, v216
	v_mov_b32_e32 v165, v225
	v_add_f32_e32 v249, 0x41a00000, v225
	v_mul_f32_e32 v166, v166, v216
	v_pk_mul_f32 v[146:147], v[146:147], v[216:217] op_sel_hi:[1,0]
	v_pk_mul_f32 v[148:149], v[148:149], v[216:217] op_sel_hi:[1,0]
	v_pk_mul_f32 v[150:151], v[150:151], v[216:217] op_sel_hi:[1,0]
	v_pk_mul_f32 v[152:153], v[152:153], v[216:217] op_sel_hi:[1,0]
	v_pk_mul_f32 v[154:155], v[154:155], v[216:217] op_sel_hi:[1,0]
	v_pk_mul_f32 v[156:157], v[156:157], v[216:217] op_sel_hi:[1,0]
	v_pk_mul_f32 v[158:159], v[158:159], v[216:217] op_sel_hi:[1,0]
	v_pk_mul_f32 v[160:161], v[160:161], v[216:217] op_sel_hi:[1,0]
	v_pk_mul_f32 v[184:185], v[184:185], v[216:217] op_sel_hi:[1,0]
	v_pk_mul_f32 v[186:187], v[186:187], v[216:217] op_sel_hi:[1,0]
	v_pk_mul_f32 v[188:189], v[188:189], v[216:217] op_sel_hi:[1,0]
	v_pk_mul_f32 v[190:191], v[190:191], v[216:217] op_sel_hi:[1,0]
	v_pk_mul_f32 v[192:193], v[192:193], v[216:217] op_sel_hi:[1,0]
	v_pk_mul_f32 v[194:195], v[194:195], v[216:217] op_sel_hi:[1,0]
	v_pk_mul_f32 v[196:197], v[196:197], v[216:217] op_sel_hi:[1,0]
	v_pk_mul_f32 v[198:199], v[198:199], v[216:217] op_sel_hi:[1,0]
.Lband_keep0:
	v_sub_f32_e32 v236, v169, v165
	v_pk_add_f32 v[200:201], v[200:201], v[236:237] op_sel_hi:[1,0]
	v_exp_f32_e32 v200, v200
	v_exp_f32_e32 v201, v201
	v_pk_add_f32 v[202:203], v[202:203], v[236:237] op_sel_hi:[1,0]
	v_exp_f32_e32 v202, v202
	v_exp_f32_e32 v203, v203
	v_pk_add_f32 v[204:205], v[204:205], v[236:237] op_sel_hi:[1,0]
	v_exp_f32_e32 v204, v204
	v_exp_f32_e32 v205, v205
	v_pk_add_f32 v[206:207], v[206:207], v[236:237] op_sel_hi:[1,0]
	v_exp_f32_e32 v206, v206
	v_exp_f32_e32 v207, v207
	v_pk_add_f32 v[208:209], v[208:209], v[236:237] op_sel_hi:[1,0]
	v_exp_f32_e32 v208, v208
	v_exp_f32_e32 v209, v209
	v_pk_add_f32 v[210:211], v[210:211], v[236:237] op_sel_hi:[1,0]
	v_exp_f32_e32 v210, v210
	v_exp_f32_e32 v211, v211
	v_pk_add_f32 v[212:213], v[212:213], v[236:237] op_sel_hi:[1,0]
	v_exp_f32_e32 v212, v212
	v_exp_f32_e32 v213, v213
	v_pk_add_f32 v[214:215], v[214:215], v[236:237] op_sel_hi:[1,0]
	v_exp_f32_e32 v214, v214
	v_exp_f32_e32 v215, v215
	v_pk_add_f32 v[236:237], v[200:201], v[202:203]
	v_pk_add_f32 v[216:217], v[204:205], v[206:207]
	v_pk_add_f32 v[236:237], v[236:237], v[208:209]
	v_pk_add_f32 v[216:217], v[216:217], v[210:211]
	v_pk_add_f32 v[236:237], v[236:237], v[212:213]
	v_pk_add_f32 v[216:217], v[216:217], v[214:215]
	v_pk_add_f32 v[236:237], v[236:237], v[216:217]
	v_add_f32_e32 v183, v236, v237
	v_add_f32_e32 v166, v166, v183
	v_cvt_pk_bf16_f32 v200, v200, v201
	v_cvt_pk_bf16_f32 v201, v202, v203
	v_cvt_pk_bf16_f32 v202, v204, v205
	v_cvt_pk_bf16_f32 v203, v206, v207
	v_cvt_pk_bf16_f32 v204, v208, v209
	v_cvt_pk_bf16_f32 v205, v210, v211
	v_cvt_pk_bf16_f32 v206, v212, v213
	v_cvt_pk_bf16_f32 v207, v214, v215
	s_waitcnt vmcnt(28)
	s_nop 1
	v_mfma_f32_32x32x16_bf16 v[146:161], v[82:85], v[200:203], v[146:161]
	v_mfma_f32_32x32x16_bf16 v[184:199], v[90:93], v[200:203], v[184:199]
	v_mfma_f32_32x32x16_bf16 v[146:161], v[86:89], v[204:207], v[146:161]
	v_mfma_f32_32x32x16_bf16 v[184:199], v[94:97], v[204:207], v[184:199]

.Lband_s1a:
	s_add_i32 s16, s8, 0
	s_max_i32 s16, s16, 0
	s_lshl_b32 s17, s16, 12
	v_add_u32_e32 v177, s17, v162
	global_load_dwordx4 v[18:21], v177, s[4:5]
	global_load_dwordx4 v[22:25], v177, s[4:5] offset:1024
	global_load_dwordx4 v[26:29], v177, s[4:5] offset:2048
	global_load_dwordx4 v[30:33], v177, s[4:5] offset:3072
	s_cmp_lt_i32 s8, 3
	s_cbranch_scc1 .Lband_s1b
	v_fmamk_f32 v169, v167, 0xc2c00000, v168
	s_nop 7
	s_nop 4
	v_pk_fma_f32 v[200:201], v[200:201], v[226:227], s[34:35] op_sel_hi:[1,0,1]
	v_pk_fma_f32 v[202:203], v[202:203], v[226:227], s[36:37] op_sel_hi:[1,0,1]
	v_pk_fma_f32 v[204:205], v[204:205], v[226:227], s[38:39] op_sel_hi:[1,0,1]
	v_pk_fma_f32 v[206:207], v[206:207], v[226:227], s[40:41] op_sel_hi:[1,0,1]
	v_pk_fma_f32 v[208:209], v[208:209], v[226:227], s[42:43] op_sel_hi:[1,0,1]
	v_pk_fma_f32 v[210:211], v[210:211], v[226:227], s[44:45] op_sel_hi:[1,0,1]
	v_pk_fma_f32 v[212:213], v[212:213], v[226:227], s[46:47] op_sel_hi:[1,0,1]
	v_pk_fma_f32 v[214:215], v[214:215], v[226:227], s[48:49] op_sel_hi:[1,0,1]
	v_max3_f32 v183, v200, v201, v202
	v_max3_f32 v225, v203, v204, v205
	v_max3_f32 v216, v206, v207, v208
	v_max3_f32 v217, v209, v210, v211
	v_max3_f32 v236, v212, v213, v214
	v_max3_f32 v183, v183, v225, v216
	v_max3_f32 v217, v217, v236, v215
	v_max_f32_e32 v183, v183, v217
	v_add_f32_e32 v183, v183, v169
	v_mov_b32_e32 v225, v183
	s_nop 1
	v_permlane32_swap_b32_e32 v225, v183
	v_max_f32_e32 v183, v183, v225
	v_cmp_lt_f32_e32 vcc, v249, v183
	s_cbranch_vccz .Lband_keep1
	v_max_f32_e32 v225, v165, v183
	v_sub_f32_e32 v216, v165, v225
	v_exp_f32_e32 v216, v216
	v_mov_b32_e32 v165, v225
	v_add_f32_e32 v249, 0x41a00000, v225
	v_mul_f32_e32 v166, v166, v216
	v_pk_mul_f32 v[146:147], v[146:147], v[216:217] op_sel_hi:[1,0]
	v_pk_mul_f32 v[148:149], v[148:149], v[216:217] op_sel_hi:[1,0]
	v_pk_mul_f32 v[150:151], v[150:151], v[216:217] op_sel_hi:[1,0]
	v_pk_mul_f32 v[152:153], v[152:153], v[216:217] op_sel_hi:[1,0]
	v_pk_mul_f32 v[154:155], v[154:155], v[216:217] op_sel_hi:[1,0]
	v_pk_mul_f32 v[156:157], v[156:157], v[216:217] op_sel_hi:[1,0]
	v_pk_mul_f32 v[158:159], v[158:159], v[216:217] op_sel_hi:[1,0]
	v_pk_mul_f32 v[160:161], v[160:161], v[216:217] op_sel_hi:[1,0]
	v_pk_mul_f32 v[184:185], v[184:185], v[216:217] op_sel_hi:[1,0]
	v_pk_mul_f32 v[186:187], v[186:187], v[216:217] op_sel_hi:[1,0]
	v_pk_mul_f32 v[188:189], v[188:189], v[216:217] op_sel_hi:[1,0]
	v_pk_mul_f32 v[190:191], v[190:191], v[216:217] op_sel_hi:[1,0]
	v_pk_mul_f32 v[192:193], v[192:193], v[216:217] op_sel_hi:[1,0]
	v_pk_mul_f32 v[194:195], v[194:195], v[216:217] op_sel_hi:[1,0]
	v_pk_mul_f32 v[196:197], v[196:197], v[216:217] op_sel_hi:[1,0]
	v_pk_mul_f32 v[198:199], v[198:199], v[216:217] op_sel_hi:[1,0]
.Lband_keep1:
	v_sub_f32_e32 v236, v169, v165
	v_pk_add_f32 v[200:201], v[200:201], v[236:237] op_sel_hi:[1,0]
	v_exp_f32_e32 v200, v200
	v_exp_f32_e32 v201, v201
	v_pk_add_f32 v[202:203], v[202:203], v[236:237] op_sel_hi:[1,0]
	v_exp_f32_e32 v202, v202
	v_exp_f32_e32 v203, v203
	v_pk_add_f32 v[204:205], v[204:205], v[236:237] op_sel_hi:[1,0]
	v_exp_f32_e32 v204, v204
	v_exp_f32_e32 v205, v205
	v_pk_add_f32 v[206:207], v[206:207], v[236:237] op_sel_hi:[1,0]
	v_exp_f32_e32 v206, v206
	v_exp_f32_e32 v207, v207
	v_pk_add_f32 v[208:209], v[208:209], v[236:237] op_sel_hi:[1,0]
	v_exp_f32_e32 v208, v208
	v_exp_f32_e32 v209, v209
	v_pk_add_f32 v[210:211], v[210:211], v[236:237] op_sel_hi:[1,0]
	v_exp_f32_e32 v210, v210
	v_exp_f32_e32 v211, v211
	v_pk_add_f32 v[212:213], v[212:213], v[236:237] op_sel_hi:[1,0]
	v_exp_f32_e32 v212, v212
	v_exp_f32_e32 v213, v213
	v_pk_add_f32 v[214:215], v[214:215], v[236:237] op_sel_hi:[1,0]
	v_exp_f32_e32 v214, v214
	v_exp_f32_e32 v215, v215
	v_pk_add_f32 v[236:237], v[200:201], v[202:203]
	v_pk_add_f32 v[216:217], v[204:205], v[206:207]
	v_pk_add_f32 v[236:237], v[236:237], v[208:209]
	v_pk_add_f32 v[216:217], v[216:217], v[210:211]
	v_pk_add_f32 v[236:237], v[236:237], v[212:213]
	v_pk_add_f32 v[216:217], v[216:217], v[214:215]
	v_pk_add_f32 v[236:237], v[236:237], v[216:217]
	v_add_f32_e32 v183, v236, v237
	v_add_f32_e32 v166, v166, v183
	v_cvt_pk_bf16_f32 v200, v200, v201
	v_cvt_pk_bf16_f32 v201, v202, v203
	v_cvt_pk_bf16_f32 v202, v204, v205
	v_cvt_pk_bf16_f32 v203, v206, v207
	v_cvt_pk_bf16_f32 v204, v208, v209
	v_cvt_pk_bf16_f32 v205, v210, v211
	v_cvt_pk_bf16_f32 v206, v212, v213
	v_cvt_pk_bf16_f32 v207, v214, v215
	s_waitcnt vmcnt(24)
	s_nop 1
	v_mfma_f32_32x32x16_bf16 v[146:161], v[98:101], v[200:203], v[146:161]
	v_mfma_f32_32x32x16_bf16 v[184:199], v[106:109], v[200:203], v[184:199]
	v_mfma_f32_32x32x16_bf16 v[146:161], v[102:105], v[204:207], v[146:161]
	v_mfma_f32_32x32x16_bf16 v[184:199], v[110:113], v[204:207], v[184:199]

.Lband_s2a:
	s_cmp_lt_i32 s8, 2
	s_cbranch_scc1 .Lband_s2b
	v_fmamk_f32 v169, v167, 0xc2800000, v168
	s_nop 7
	s_nop 4
	v_pk_fma_f32 v[200:201], v[200:201], v[226:227], s[34:35] op_sel_hi:[1,0,1]
	v_pk_fma_f32 v[202:203], v[202:203], v[226:227], s[36:37] op_sel_hi:[1,0,1]
	v_pk_fma_f32 v[204:205], v[204:205], v[226:227], s[38:39] op_sel_hi:[1,0,1]
	v_pk_fma_f32 v[206:207], v[206:207], v[226:227], s[40:41] op_sel_hi:[1,0,1]
	v_pk_fma_f32 v[208:209], v[208:209], v[226:227], s[42:43] op_sel_hi:[1,0,1]
	v_pk_fma_f32 v[210:211], v[210:211], v[226:227], s[44:45] op_sel_hi:[1,0,1]
	v_pk_fma_f32 v[212:213], v[212:213], v[226:227], s[46:47] op_sel_hi:[1,0,1]
	v_pk_fma_f32 v[214:215], v[214:215], v[226:227], s[48:49] op_sel_hi:[1,0,1]
	v_max3_f32 v183, v200, v201, v202
	v_max3_f32 v225, v203, v204, v205
	v_max3_f32 v216, v206, v207, v208
	v_max3_f32 v217, v209, v210, v211
	v_max3_f32 v236, v212, v213, v214
	v_max3_f32 v183, v183, v225, v216
	v_max3_f32 v217, v217, v236, v215
	v_max_f32_e32 v183, v183, v217
	v_add_f32_e32 v183, v183, v169
	v_mov_b32_e32 v225, v183
	s_nop 1
	v_permlane32_swap_b32_e32 v225, v183
	v_max_f32_e32 v183, v183, v225
	v_cmp_lt_f32_e32 vcc, v249, v183
	s_cbranch_vccz .Lband_keep2
	v_max_f32_e32 v225, v165, v183
	v_sub_f32_e32 v216, v165, v225
	v_exp_f32_e32 v216, v216
	v_mov_b32_e32 v165, v225
	v_add_f32_e32 v249, 0x41a00000, v225
	v_mul_f32_e32 v166, v166, v216
	v_pk_mul_f32 v[146:147], v[146:147], v[216:217] op_sel_hi:[1,0]
	v_pk_mul_f32 v[148:149], v[148:149], v[216:217] op_sel_hi:[1,0]
	v_pk_mul_f32 v[150:151], v[150:151], v[216:217] op_sel_hi:[1,0]
	v_pk_mul_f32 v[152:153], v[152:153], v[216:217] op_sel_hi:[1,0]
	v_pk_mul_f32 v[154:155], v[154:155], v[216:217] op_sel_hi:[1,0]
	v_pk_mul_f32 v[156:157], v[156:157], v[216:217] op_sel_hi:[1,0]
	v_pk_mul_f32 v[158:159], v[158:159], v[216:217] op_sel_hi:[1,0]
	v_pk_mul_f32 v[160:161], v[160:161], v[216:217] op_sel_hi:[1,0]
	v_pk_mul_f32 v[184:185], v[184:185], v[216:217] op_sel_hi:[1,0]
	v_pk_mul_f32 v[186:187], v[186:187], v[216:217] op_sel_hi:[1,0]
	v_pk_mul_f32 v[188:189], v[188:189], v[216:217] op_sel_hi:[1,0]
	v_pk_mul_f32 v[190:191], v[190:191], v[216:217] op_sel_hi:[1,0]
	v_pk_mul_f32 v[192:193], v[192:193], v[216:217] op_sel_hi:[1,0]
	v_pk_mul_f32 v[194:195], v[194:195], v[216:217] op_sel_hi:[1,0]
	v_pk_mul_f32 v[196:197], v[196:197], v[216:217] op_sel_hi:[1,0]
	v_pk_mul_f32 v[198:199], v[198:199], v[216:217] op_sel_hi:[1,0]
.Lband_keep2:
	v_sub_f32_e32 v236, v169, v165
	v_pk_add_f32 v[200:201], v[200:201], v[236:237] op_sel_hi:[1,0]
	v_exp_f32_e32 v200, v200
	v_exp_f32_e32 v201, v201
	v_pk_add_f32 v[202:203], v[202:203], v[236:237] op_sel_hi:[1,0]
	v_exp_f32_e32 v202, v202
	v_exp_f32_e32 v203, v203
	v_pk_add_f32 v[204:205], v[204:205], v[236:237] op_sel_hi:[1,0]
	v_exp_f32_e32 v204, v204
	v_exp_f32_e32 v205, v205
	v_pk_add_f32 v[206:207], v[206:207], v[236:237] op_sel_hi:[1,0]
	v_exp_f32_e32 v206, v206
	v_exp_f32_e32 v207, v207
	v_pk_add_f32 v[208:209], v[208:209], v[236:237] op_sel_hi:[1,0]
	v_exp_f32_e32 v208, v208
	v_exp_f32_e32 v209, v209
	v_pk_add_f32 v[210:211], v[210:211], v[236:237] op_sel_hi:[1,0]
	v_exp_f32_e32 v210, v210
	v_exp_f32_e32 v211, v211
	v_pk_add_f32 v[212:213], v[212:213], v[236:237] op_sel_hi:[1,0]
	v_exp_f32_e32 v212, v212
	v_exp_f32_e32 v213, v213
	v_pk_add_f32 v[214:215], v[214:215], v[236:237] op_sel_hi:[1,0]
	v_exp_f32_e32 v214, v214
	v_exp_f32_e32 v215, v215
	v_pk_add_f32 v[236:237], v[200:201], v[202:203]
	v_pk_add_f32 v[216:217], v[204:205], v[206:207]
	v_pk_add_f32 v[236:237], v[236:237], v[208:209]
	v_pk_add_f32 v[216:217], v[216:217], v[210:211]
	v_pk_add_f32 v[236:237], v[236:237], v[212:213]
	v_pk_add_f32 v[216:217], v[216:217], v[214:215]
	v_pk_add_f32 v[236:237], v[236:237], v[216:217]
	v_add_f32_e32 v183, v236, v237
	v_add_f32_e32 v166, v166, v183
	v_cvt_pk_bf16_f32 v200, v200, v201
	v_cvt_pk_bf16_f32 v201, v202, v203
	v_cvt_pk_bf16_f32 v202, v204, v205
	v_cvt_pk_bf16_f32 v203, v206, v207
	v_cvt_pk_bf16_f32 v204, v208, v209
	v_cvt_pk_bf16_f32 v205, v210, v211
	v_cvt_pk_bf16_f32 v206, v212, v213
	v_cvt_pk_bf16_f32 v207, v214, v215
	s_waitcnt vmcnt(16)
	s_nop 1
	v_mfma_f32_32x32x16_bf16 v[146:161], v[114:117], v[200:203], v[146:161]
	v_mfma_f32_32x32x16_bf16 v[184:199], v[122:125], v[200:203], v[184:199]
	v_mfma_f32_32x32x16_bf16 v[146:161], v[118:121], v[204:207], v[146:161]
	v_mfma_f32_32x32x16_bf16 v[184:199], v[126:129], v[204:207], v[184:199]

.Lband_s3a:
	s_cmp_lt_i32 s8, 1
	s_cbranch_scc1 .Lband_s3b
	v_fmamk_f32 v169, v167, 0xc2000000, v168
	s_nop 7
	s_nop 4
	v_pk_fma_f32 v[200:201], v[200:201], v[226:227], s[34:35] op_sel_hi:[1,0,1]
	v_pk_fma_f32 v[202:203], v[202:203], v[226:227], s[36:37] op_sel_hi:[1,0,1]
	v_pk_fma_f32 v[204:205], v[204:205], v[226:227], s[38:39] op_sel_hi:[1,0,1]
	v_pk_fma_f32 v[206:207], v[206:207], v[226:227], s[40:41] op_sel_hi:[1,0,1]
	v_pk_fma_f32 v[208:209], v[208:209], v[226:227], s[42:43] op_sel_hi:[1,0,1]
	v_pk_fma_f32 v[210:211], v[210:211], v[226:227], s[44:45] op_sel_hi:[1,0,1]
	v_pk_fma_f32 v[212:213], v[212:213], v[226:227], s[46:47] op_sel_hi:[1,0,1]
	v_pk_fma_f32 v[214:215], v[214:215], v[226:227], s[48:49] op_sel_hi:[1,0,1]
	v_max3_f32 v183, v200, v201, v202
	v_max3_f32 v225, v203, v204, v205
	v_max3_f32 v216, v206, v207, v208
	v_max3_f32 v217, v209, v210, v211
	v_max3_f32 v236, v212, v213, v214
	v_max3_f32 v183, v183, v225, v216
	v_max3_f32 v217, v217, v236, v215
	v_max_f32_e32 v183, v183, v217
	v_add_f32_e32 v183, v183, v169
	v_mov_b32_e32 v225, v183
	s_nop 1
	v_permlane32_swap_b32_e32 v225, v183
	v_max_f32_e32 v183, v183, v225
	v_cmp_lt_f32_e32 vcc, v249, v183
	s_cbranch_vccz .Lband_keep3
	v_max_f32_e32 v225, v165, v183
	v_sub_f32_e32 v216, v165, v225
	v_exp_f32_e32 v216, v216
	v_mov_b32_e32 v165, v225
	v_add_f32_e32 v249, 0x41a00000, v225
	v_mul_f32_e32 v166, v166, v216
	v_pk_mul_f32 v[146:147], v[146:147], v[216:217] op_sel_hi:[1,0]
	v_pk_mul_f32 v[148:149], v[148:149], v[216:217] op_sel_hi:[1,0]
	v_pk_mul_f32 v[150:151], v[150:151], v[216:217] op_sel_hi:[1,0]
	v_pk_mul_f32 v[152:153], v[152:153], v[216:217] op_sel_hi:[1,0]
	v_pk_mul_f32 v[154:155], v[154:155], v[216:217] op_sel_hi:[1,0]
	v_pk_mul_f32 v[156:157], v[156:157], v[216:217] op_sel_hi:[1,0]
	v_pk_mul_f32 v[158:159], v[158:159], v[216:217] op_sel_hi:[1,0]
	v_pk_mul_f32 v[160:161], v[160:161], v[216:217] op_sel_hi:[1,0]
	v_pk_mul_f32 v[184:185], v[184:185], v[216:217] op_sel_hi:[1,0]
	v_pk_mul_f32 v[186:187], v[186:187], v[216:217] op_sel_hi:[1,0]
	v_pk_mul_f32 v[188:189], v[188:189], v[216:217] op_sel_hi:[1,0]
	v_pk_mul_f32 v[190:191], v[190:191], v[216:217] op_sel_hi:[1,0]
	v_pk_mul_f32 v[192:193], v[192:193], v[216:217] op_sel_hi:[1,0]
	v_pk_mul_f32 v[194:195], v[194:195], v[216:217] op_sel_hi:[1,0]
	v_pk_mul_f32 v[196:197], v[196:197], v[216:217] op_sel_hi:[1,0]
	v_pk_mul_f32 v[198:199], v[198:199], v[216:217] op_sel_hi:[1,0]
.Lband_keep3:
	v_sub_f32_e32 v236, v169, v165
	v_pk_add_f32 v[200:201], v[200:201], v[236:237] op_sel_hi:[1,0]
	v_exp_f32_e32 v200, v200
	v_exp_f32_e32 v201, v201
	v_pk_add_f32 v[202:203], v[202:203], v[236:237] op_sel_hi:[1,0]
	v_exp_f32_e32 v202, v202
	v_exp_f32_e32 v203, v203
	v_pk_add_f32 v[204:205], v[204:205], v[236:237] op_sel_hi:[1,0]
	v_exp_f32_e32 v204, v204
	v_exp_f32_e32 v205, v205
	v_pk_add_f32 v[206:207], v[206:207], v[236:237] op_sel_hi:[1,0]
	v_exp_f32_e32 v206, v206
	v_exp_f32_e32 v207, v207
	v_pk_add_f32 v[208:209], v[208:209], v[236:237] op_sel_hi:[1,0]
	v_exp_f32_e32 v208, v208
	v_exp_f32_e32 v209, v209
	v_pk_add_f32 v[210:211], v[210:211], v[236:237] op_sel_hi:[1,0]
	v_exp_f32_e32 v210, v210
	v_exp_f32_e32 v211, v211
	v_pk_add_f32 v[212:213], v[212:213], v[236:237] op_sel_hi:[1,0]
	v_exp_f32_e32 v212, v212
	v_exp_f32_e32 v213, v213
	v_pk_add_f32 v[214:215], v[214:215], v[236:237] op_sel_hi:[1,0]
	v_exp_f32_e32 v214, v214
	v_exp_f32_e32 v215, v215
	v_pk_add_f32 v[236:237], v[200:201], v[202:203]
	v_pk_add_f32 v[216:217], v[204:205], v[206:207]
	v_pk_add_f32 v[236:237], v[236:237], v[208:209]
	v_pk_add_f32 v[216:217], v[216:217], v[210:211]
	v_pk_add_f32 v[236:237], v[236:237], v[212:213]
	v_pk_add_f32 v[216:217], v[216:217], v[214:215]
	v_pk_add_f32 v[236:237], v[236:237], v[216:217]
	v_add_f32_e32 v183, v236, v237
	v_add_f32_e32 v166, v166, v183
	v_cvt_pk_bf16_f32 v200, v200, v201
	v_cvt_pk_bf16_f32 v201, v202, v203
	v_cvt_pk_bf16_f32 v202, v204, v205
	v_cvt_pk_bf16_f32 v203, v206, v207
	v_cvt_pk_bf16_f32 v204, v208, v209
	v_cvt_pk_bf16_f32 v205, v210, v211
	v_cvt_pk_bf16_f32 v206, v212, v213
	v_cvt_pk_bf16_f32 v207, v214, v215
	s_waitcnt vmcnt(4)
	s_nop 1
	v_mfma_f32_32x32x16_bf16 v[146:161], v[2:5], v[200:203], v[146:161]
	v_mfma_f32_32x32x16_bf16 v[184:199], v[10:13], v[200:203], v[184:199]
	v_mfma_f32_32x32x16_bf16 v[146:161], v[6:9], v[204:207], v[146:161]
	v_mfma_f32_32x32x16_bf16 v[184:199], v[14:17], v[204:207], v[184:199]
.Lband_s3b:
	s_waitcnt vmcnt(8)
	v_mfma_f32_32x32x16_bf16 v[200:215], v[66:69], v[130:133], 0
	v_mfma_f32_32x32x16_bf16 v[200:215], v[70:73], v[134:137], v[200:215]
	v_mfma_f32_32x32x16_bf16 v[200:215], v[74:77], v[138:141], v[200:215]
	v_mfma_f32_32x32x16_bf16 v[200:215], v[78:81], v[142:145], v[200:215]
	v_mov_b32_e32 v169, v168
	s_nop 7
	s_nop 4
	v_pk_fma_f32 v[200:201], v[200:201], v[226:227], s[34:35] op_sel_hi:[1,0,1]
	v_pk_fma_f32 v[202:203], v[202:203], v[226:227], s[36:37] op_sel_hi:[1,0,1]
	v_pk_fma_f32 v[204:205], v[204:205], v[226:227], s[38:39] op_sel_hi:[1,0,1]
	v_pk_fma_f32 v[206:207], v[206:207], v[226:227], s[40:41] op_sel_hi:[1,0,1]
	v_pk_fma_f32 v[208:209], v[208:209], v[226:227], s[42:43] op_sel_hi:[1,0,1]
	v_pk_fma_f32 v[210:211], v[210:211], v[226:227], s[44:45] op_sel_hi:[1,0,1]
	v_pk_fma_f32 v[212:213], v[212:213], v[226:227], s[46:47] op_sel_hi:[1,0,1]
	v_pk_fma_f32 v[214:215], v[214:215], v[226:227], s[48:49] op_sel_hi:[1,0,1]
	v_cmp_le_i32_e64 s[16:17], 0, v170
	v_cmp_le_i32_e64 s[22:23], 1, v170
	v_cmp_le_i32_e64 s[24:25], 2, v170
	v_cmp_le_i32_e64 s[28:29], 3, v170
	v_cmp_le_i32_e32 vcc, 8, v170
	v_cndmask_b32_e64 v200, v227, v200, s[16:17]
	v_cndmask_b32_e64 v201, v227, v201, s[22:23]
	v_cndmask_b32_e64 v202, v227, v202, s[24:25]
	v_cndmask_b32_e64 v203, v227, v203, s[28:29]
	v_cndmask_b32_e64 v204, v227, v204, vcc
	v_cmp_le_i32_e64 s[16:17], 9, v170
	v_cmp_le_i32_e64 s[22:23], 10, v170
	v_cmp_le_i32_e64 s[24:25], 11, v170
	v_cmp_le_i32_e64 s[28:29], 16, v170
	v_cmp_le_i32_e32 vcc, 17, v170
	v_cndmask_b32_e64 v205, v227, v205, s[16:17]
	v_cndmask_b32_e64 v206, v227, v206, s[22:23]
	v_cndmask_b32_e64 v207, v227, v207, s[24:25]
	v_cndmask_b32_e64 v208, v227, v208, s[28:29]
	v_cndmask_b32_e64 v209, v227, v209, vcc
	v_cmp_le_i32_e64 s[16:17], 18, v170
	v_cmp_le_i32_e64 s[22:23], 19, v170
	v_cmp_le_i32_e64 s[24:25], 24, v170
	v_cmp_le_i32_e64 s[28:29], 25, v170
	v_cmp_le_i32_e32 vcc, 26, v170
	v_cndmask_b32_e64 v210, v227, v210, s[16:17]
	v_cndmask_b32_e64 v211, v227, v211, s[22:23]
	v_cndmask_b32_e64 v212, v227, v212, s[24:25]
	v_cndmask_b32_e64 v213, v227, v213, s[28:29]
	v_cndmask_b32_e64 v214, v227, v214, vcc
	v_cmp_le_i32_e64 s[16:17], 27, v170
	s_nop 1
	v_cndmask_b32_e64 v215, v227, v215, s[16:17]
	v_max3_f32 v183, v200, v201, v202
	v_max3_f32 v225, v203, v204, v205
	v_max3_f32 v216, v206, v207, v208
	v_max3_f32 v217, v209, v210, v211
	v_max3_f32 v236, v212, v213, v214
	v_max3_f32 v183, v183, v225, v216
	v_max3_f32 v217, v217, v236, v215
	v_max_f32_e32 v183, v183, v217
	v_add_f32_e32 v183, v183, v169
	v_mov_b32_e32 v225, v183
	s_nop 1
	v_permlane32_swap_b32_e32 v225, v183
	v_max_f32_e32 v183, v183, v225
	v_cmp_lt_f32_e32 vcc, v249, v183
	s_cbranch_vccz .Lband_keep4
	v_max_f32_e32 v225, v165, v183
	v_sub_f32_e32 v216, v165, v225
	v_exp_f32_e32 v216, v216
	v_mov_b32_e32 v165, v225
	v_add_f32_e32 v249, 0x41a00000, v225
	v_mul_f32_e32 v166, v166, v216
	v_pk_mul_f32 v[146:147], v[146:147], v[216:217] op_sel_hi:[1,0]
	v_pk_mul_f32 v[148:149], v[148:149], v[216:217] op_sel_hi:[1,0]
	v_pk_mul_f32 v[150:151], v[150:151], v[216:217] op_sel_hi:[1,0]
	v_pk_mul_f32 v[152:153], v[152:153], v[216:217] op_sel_hi:[1,0]
	v_pk_mul_f32 v[154:155], v[154:155], v[216:217] op_sel_hi:[1,0]
	v_pk_mul_f32 v[156:157], v[156:157], v[216:217] op_sel_hi:[1,0]
	v_pk_mul_f32 v[158:159], v[158:159], v[216:217] op_sel_hi:[1,0]
	v_pk_mul_f32 v[160:161], v[160:161], v[216:217] op_sel_hi:[1,0]
	v_pk_mul_f32 v[184:185], v[184:185], v[216:217] op_sel_hi:[1,0]
	v_pk_mul_f32 v[186:187], v[186:187], v[216:217] op_sel_hi:[1,0]
	v_pk_mul_f32 v[188:189], v[188:189], v[216:217] op_sel_hi:[1,0]
	v_pk_mul_f32 v[190:191], v[190:191], v[216:217] op_sel_hi:[1,0]
	v_pk_mul_f32 v[192:193], v[192:193], v[216:217] op_sel_hi:[1,0]
	v_pk_mul_f32 v[194:195], v[194:195], v[216:217] op_sel_hi:[1,0]
	v_pk_mul_f32 v[196:197], v[196:197], v[216:217] op_sel_hi:[1,0]
	v_pk_mul_f32 v[198:199], v[198:199], v[216:217] op_sel_hi:[1,0]
.Lband_keep4:
	v_sub_f32_e32 v236, v169, v165
	v_pk_add_f32 v[200:201], v[200:201], v[236:237] op_sel_hi:[1,0]
	v_exp_f32_e32 v200, v200
	v_exp_f32_e32 v201, v201
	v_pk_add_f32 v[202:203], v[202:203], v[236:237] op_sel_hi:[1,0]
	v_exp_f32_e32 v202, v202
	v_exp_f32_e32 v203, v203
	v_pk_add_f32 v[204:205], v[204:205], v[236:237] op_sel_hi:[1,0]
	v_exp_f32_e32 v204, v204
	v_exp_f32_e32 v205, v205
	v_pk_add_f32 v[206:207], v[206:207], v[236:237] op_sel_hi:[1,0]
	v_exp_f32_e32 v206, v206
	v_exp_f32_e32 v207, v207
	v_pk_add_f32 v[208:209], v[208:209], v[236:237] op_sel_hi:[1,0]
	v_exp_f32_e32 v208, v208
	v_exp_f32_e32 v209, v209
	v_pk_add_f32 v[210:211], v[210:211], v[236:237] op_sel_hi:[1,0]
	v_exp_f32_e32 v210, v210
	v_exp_f32_e32 v211, v211
	v_pk_add_f32 v[212:213], v[212:213], v[236:237] op_sel_hi:[1,0]
	v_exp_f32_e32 v212, v212
	v_exp_f32_e32 v213, v213
	v_pk_add_f32 v[214:215], v[214:215], v[236:237] op_sel_hi:[1,0]
	v_exp_f32_e32 v214, v214
	v_exp_f32_e32 v215, v215
	v_pk_add_f32 v[236:237], v[200:201], v[202:203]
	v_pk_add_f32 v[216:217], v[204:205], v[206:207]
	v_pk_add_f32 v[236:237], v[236:237], v[208:209]
	v_pk_add_f32 v[216:217], v[216:217], v[210:211]
	v_pk_add_f32 v[236:237], v[236:237], v[212:213]
	v_pk_add_f32 v[216:217], v[216:217], v[214:215]
	v_pk_add_f32 v[236:237], v[236:237], v[216:217]
	v_add_f32_e32 v183, v236, v237
	v_add_f32_e32 v166, v166, v183
	v_cvt_pk_bf16_f32 v200, v200, v201
	v_cvt_pk_bf16_f32 v201, v202, v203
	v_cvt_pk_bf16_f32 v202, v204, v205
	v_cvt_pk_bf16_f32 v203, v206, v207
	v_cvt_pk_bf16_f32 v204, v208, v209
	v_cvt_pk_bf16_f32 v205, v210, v211
	v_cvt_pk_bf16_f32 v206, v212, v213
	v_cvt_pk_bf16_f32 v207, v214, v215
	s_waitcnt vmcnt(0)
	s_nop 1
	v_mfma_f32_32x32x16_bf16 v[146:161], v[18:21], v[200:203], v[146:161]
	v_mfma_f32_32x32x16_bf16 v[184:199], v[26:29], v[200:203], v[184:199]
	v_mfma_f32_32x32x16_bf16 v[146:161], v[22:25], v[204:207], v[146:161]
	v_mfma_f32_32x32x16_bf16 v[184:199], v[30:33], v[204:207], v[184:199]
	s_nop 7
	s_nop 7
	v_mov_b32_e32 v225, v166
	s_nop 1
	v_permlane32_swap_b32_e32 v225, v166
	v_add_f32_e32 v166, v166, v225
	v_log_f32_e32 v183, v166
	v_rcp_f32_e32 v225, v166
	s_nop 0
	v_fma_f32 v216, -v166, v225, 1.0
	v_fma_f32 v225, v225, v216, v225
	v_add_f32_e32 v183, v165, v183
	v_mul_f32_e32 v183, 0x3f317218, v183
	s_cmp_eq_u32 s1, 0
	s_cbranch_scc1 .Lband_epi_swa
	v_mov_b32_e32 v216, v225
	v_cmp_eq_u32_e32 vcc, 0, v164
	s_and_saveexec_b64 s[16:17], vcc
	global_store_dword v219, v183, s[26:27]
	s_or_b64 exec, exec, s[16:17]
	s_branch .Lband_epi_scale

.Lband_epi_scale:
	v_pk_mul_f32 v[146:147], v[146:147], v[216:217] op_sel_hi:[1,0]
	v_pk_mul_f32 v[148:149], v[148:149], v[216:217] op_sel_hi:[1,0]
	v_pk_mul_f32 v[150:151], v[150:151], v[216:217] op_sel_hi:[1,0]
	v_pk_mul_f32 v[152:153], v[152:153], v[216:217] op_sel_hi:[1,0]
	v_pk_mul_f32 v[154:155], v[154:155], v[216:217] op_sel_hi:[1,0]
	v_pk_mul_f32 v[156:157], v[156:157], v[216:217] op_sel_hi:[1,0]
	v_pk_mul_f32 v[158:159], v[158:159], v[216:217] op_sel_hi:[1,0]
	v_pk_mul_f32 v[160:161], v[160:161], v[216:217] op_sel_hi:[1,0]
	v_pk_mul_f32 v[184:185], v[184:185], v[216:217] op_sel_hi:[1,0]
	v_pk_mul_f32 v[186:187], v[186:187], v[216:217] op_sel_hi:[1,0]
	v_pk_mul_f32 v[188:189], v[188:189], v[216:217] op_sel_hi:[1,0]
	v_pk_mul_f32 v[190:191], v[190:191], v[216:217] op_sel_hi:[1,0]
	v_pk_mul_f32 v[192:193], v[192:193], v[216:217] op_sel_hi:[1,0]
	v_pk_mul_f32 v[194:195], v[194:195], v[216:217] op_sel_hi:[1,0]
	v_pk_mul_f32 v[196:197], v[196:197], v[216:217] op_sel_hi:[1,0]
	v_pk_mul_f32 v[198:199], v[198:199], v[216:217] op_sel_hi:[1,0]
	v_cvt_pk_bf16_f32 v146, v146, v147
	v_cvt_pk_bf16_f32 v147, v148, v149
	global_store_dwordx2 v218, v[146:147], s[6:7]
	v_cvt_pk_bf16_f32 v150, v150, v151
	v_cvt_pk_bf16_f32 v151, v152, v153
	global_store_dwordx2 v218, v[150:151], s[6:7] offset:16
	v_cvt_pk_bf16_f32 v154, v154, v155
	v_cvt_pk_bf16_f32 v155, v156, v157
	global_store_dwordx2 v218, v[154:155], s[6:7] offset:32
	v_cvt_pk_bf16_f32 v158, v158, v159
	v_cvt_pk_bf16_f32 v159, v160, v161
	global_store_dwordx2 v218, v[158:159], s[6:7] offset:48
	v_cvt_pk_bf16_f32 v184, v184, v185
	v_cvt_pk_bf16_f32 v185, v186, v187
	global_store_dwordx2 v218, v[184:185], s[6:7] offset:64
	v_cvt_pk_bf16_f32 v188, v188, v189
	v_cvt_pk_bf16_f32 v189, v190, v191
	global_store_dwordx2 v218, v[188:189], s[6:7] offset:80
	v_cvt_pk_bf16_f32 v192, v192, v193
	v_cvt_pk_bf16_f32 v193, v194, v195
	global_store_dwordx2 v218, v[192:193], s[6:7] offset:96
	v_cvt_pk_bf16_f32 v196, v196, v197
	v_cvt_pk_bf16_f32 v197, v198, v199
	global_store_dwordx2 v218, v[196:197], s[6:7] offset:112
	s_add_i32 s0, s0, s68
	s_cmp_lt_u32 s0, 0x4000
	s_cbranch_scc1 .Lband_item
	v_lshlrev_b32_e32 v183, 2, v220
	v_add_u32_e32 v2, 0x10000, v183
	ds_read_b32 v162, v183 offset:0
	ds_read_b32 v163, v183 offset:2048
	ds_read_b32 v164, v183 offset:4096
	ds_read_b32 v165, v183 offset:6144
	ds_read_b32 v166, v183 offset:8192
	ds_read_b32 v167, v183 offset:10240
	ds_read_b32 v168, v183 offset:12288
	ds_read_b32 v169, v183 offset:14336
	ds_read_b32 v170, v183 offset:16384
	ds_read_b32 v174, v183 offset:18432
	ds_read_b32 v175, v183 offset:20480
	ds_read_b32 v176, v183 offset:22528
	ds_read_b32 v177, v183 offset:24576
	ds_read_b32 v216, v183 offset:26624
	ds_read_b32 v217, v183 offset:28672
	ds_read_b32 v218, v183 offset:30720
	ds_read_b32 v219, v183 offset:32768
	ds_read_b32 v225, v183 offset:34816
	ds_read_b32 v226, v183 offset:36864
	ds_read_b32 v227, v183 offset:38912
	ds_read_b32 v236, v183 offset:40960
	ds_read_b32 v237, v183 offset:43008
	ds_read_b32 v249, v183 offset:45056
	ds_read_b32 v200, v183 offset:47104
	ds_read_b32 v201, v183 offset:49152
	ds_read_b32 v202, v183 offset:51200
	ds_read_b32 v203, v183 offset:53248
	ds_read_b32 v204, v183 offset:55296
	ds_read_b32 v205, v183 offset:57344
	ds_read_b32 v206, v183 offset:59392
	ds_read_b32 v207, v183 offset:61440
	ds_read_b32 v208, v183 offset:63488
	ds_read_b32 v209, v2 offset:0
	ds_read_b32 v210, v2 offset:2048
	ds_read_b32 v211, v2 offset:4096
	ds_read_b32 v212, v2 offset:6144
	ds_read_b32 v213, v2 offset:8192
	ds_read_b32 v214, v2 offset:10240
	ds_read_b32 v215, v2 offset:12288
	v_lshrrev_b32_e32 v183, 6, v220
	v_lshlrev_b32_e32 v183, 8, v183
	v_add_u32_e32 v183, 0x13800, v183
	ds_read_b32 v2, v183 offset:0
	ds_read_b32 v3, v183 offset:4
	ds_read_b32 v4, v183 offset:8
	ds_read_b32 v5, v183 offset:12
	ds_read_b32 v6, v183 offset:16
	ds_read_b32 v7, v183 offset:20
	ds_read_b32 v8, v183 offset:24
	ds_read_b32 v9, v183 offset:28
	ds_read_b32 v10, v183 offset:32
	ds_read_b32 v11, v183 offset:36
	ds_read_b32 v12, v183 offset:40
	ds_read_b32 v13, v183 offset:44
	ds_read_b32 v14, v183 offset:48
	ds_read_b32 v15, v183 offset:52
	ds_read_b32 v16, v183 offset:56
	ds_read_b32 v17, v183 offset:60
	ds_read_b32 v18, v183 offset:64
	ds_read_b32 v19, v183 offset:68
	ds_read_b32 v20, v183 offset:72
	ds_read_b32 v21, v183 offset:76
	ds_read_b32 v22, v183 offset:80
	ds_read_b32 v23, v183 offset:84
	ds_read_b32 v24, v183 offset:88
	ds_read_b32 v25, v183 offset:92
	ds_read_b32 v26, v183 offset:96
	ds_read_b32 v27, v183 offset:100
	ds_read_b32 v28, v183 offset:104
	ds_read_b32 v29, v183 offset:108
	ds_read_b32 v30, v183 offset:112
	ds_read_b32 v31, v183 offset:116
	ds_read_b32 v32, v183 offset:120
	ds_read_b32 v33, v183 offset:124
	ds_read_b32 v34, v183 offset:128
	ds_read_b32 v35, v183 offset:132
	ds_read_b32 v36, v183 offset:136
	ds_read_b32 v37, v183 offset:140
	ds_read_b32 v38, v183 offset:144
	ds_read_b32 v39, v183 offset:148
	ds_read_b32 v40, v183 offset:152
	ds_read_b32 v41, v183 offset:156
	ds_read_b32 v42, v183 offset:160
	ds_read_b32 v43, v183 offset:164
	ds_read_b32 v44, v183 offset:168
	ds_read_b32 v45, v183 offset:172
	ds_read_b32 v46, v183 offset:176
	s_waitcnt lgkmcnt(0)
	v_readfirstlane_b32 s2, v2
	v_readfirstlane_b32 s3, v3
	v_readfirstlane_b32 s4, v4
	v_readfirstlane_b32 s5, v5
	v_readfirstlane_b32 s6, v6
	v_readfirstlane_b32 s7, v7
	v_readfirstlane_b32 s8, v8
	v_readfirstlane_b32 s9, v9
	v_readfirstlane_b32 s10, v10
	v_readfirstlane_b32 s11, v11
	v_readfirstlane_b32 s12, v12
	v_readfirstlane_b32 s13, v13
	v_readfirstlane_b32 s14, v14
	v_readfirstlane_b32 s15, v15
	v_readfirstlane_b32 s16, v16
	v_readfirstlane_b32 s17, v17
	v_readfirstlane_b32 s18, v18
	v_readfirstlane_b32 s19, v19
	v_readfirstlane_b32 s20, v20
	v_readfirstlane_b32 s21, v21
	v_readfirstlane_b32 s22, v22
	v_readfirstlane_b32 s23, v23
	v_readfirstlane_b32 s24, v24
	v_readfirstlane_b32 s25, v25
	v_readfirstlane_b32 s26, v26
	v_readfirstlane_b32 s27, v27
	v_readfirstlane_b32 s28, v28
	v_readfirstlane_b32 s29, v29
	v_readfirstlane_b32 s30, v30
	v_readfirstlane_b32 s34, v31
	v_readfirstlane_b32 s35, v32
	v_readfirstlane_b32 s36, v33
	v_readfirstlane_b32 s37, v34
	v_readfirstlane_b32 s38, v35
	v_readfirstlane_b32 s39, v36
	v_readfirstlane_b32 s40, v37
	v_readfirstlane_b32 s41, v38
	v_readfirstlane_b32 s42, v39
	v_readfirstlane_b32 s43, v40
	v_readfirstlane_b32 s44, v41
	v_readfirstlane_b32 s45, v42
	v_readfirstlane_b32 s46, v43
	v_readfirstlane_b32 s47, v44
	v_readfirstlane_b32 s48, v45
	v_readfirstlane_b32 s49, v46
	s_waitcnt vmcnt(0)
	s_branch .Lband_exit
